# nt on P0 XB stores, second measurement
# speedup vs baseline: 1.0124x; 1.0077x over previous
; __device__ __forceinline__ unsigned pk2(float lo, float hi) { unsigned r; asm("v_cvt_pk_bf16_f32 %0, %1, %2" : "=v"(r) : "v"(lo), "v"(hi)); return r; }
; __device__ __forceinline__ float bflo(unsigned w) { return __uint_as_float(w << 16); }
; __device__ __forceinline__ float bfhi(unsigned w) { return __uint_as_float(w & 0xffff0000u); }
; __global__ void __launch_bounds__(512, 2) mk_fwd(Params p) {
;     ...
;             for (int m = gw; m < M; m += NGW) {
;                 const f32x4* xr = (const f32x4*)(p.x + (size_t)m * DM) + lane; v2u* o8 = (v2u*)(XB + (size_t)m * DM) + lane; float sq = 0.f;
; #pragma unroll
;                 for (int j = 0; j < 8; ++j) { const f32x4 v = xr[64 * j]; v2u w; w.x = pk2(v.x, v.y); w.y = pk2(v.z, v.w); o8[64 * j] = w;
;                     const float r0 = bflo(w.x), r1 = bfhi(w.x), r2 = bflo(w.y), r3 = bfhi(w.y); sq += (r0 * r0 + r1 * r1) + (r2 * r2 + r3 * r3); }
;                 sq = wave_sum(sq); if (lane < 32) ROWSQ[(size_t)m * 32 + lane] = (lane == 0) ? sq : 0.f;
.LBB0_252:
	v_add_co_u32_e32 v12, vcc, 0xfffff000, v6
	s_nop 1
	v_addc_co_u32_e32 v13, vcc, -1, v7, vcc
	s_waitcnt lgkmcnt(0)
	global_load_dwordx4 v[8:11], v[12:13], off offset:-3072 nt
	s_waitcnt vmcnt(0)
	v_cvt_pk_bf16_f32 v14, v8, v9
	v_cvt_pk_bf16_f32 v15, v10, v11
	global_store_dwordx2 v[2:3], v[14:15], off offset:-2048 nt
	v_lshlrev_b32_e32 v26, 16, v14
	v_and_b32_e32 v14, 0xffff0000, v14
	v_lshlrev_b32_e32 v27, 16, v15
	v_and_b32_e32 v15, 0xffff0000, v15
	v_mul_f32_e32 v14, v14, v14
	v_mul_f32_e32 v15, v15, v15
	global_load_dwordx4 v[8:11], v[12:13], off offset:-2048 nt
	s_waitcnt vmcnt(0)
	v_cvt_pk_bf16_f32 v16, v8, v9
	v_cvt_pk_bf16_f32 v17, v10, v11
	v_fmac_f32_e32 v14, v26, v26
	v_fmac_f32_e32 v15, v27, v27
	global_store_dwordx2 v[2:3], v[16:17], off offset:-1536 nt
	v_add_f32_e32 v14, v14, v15
	v_lshlrev_b32_e32 v15, 16, v16
	v_and_b32_e32 v16, 0xffff0000, v16
	v_lshlrev_b32_e32 v26, 16, v17
	v_and_b32_e32 v17, 0xffff0000, v17
	v_mul_f32_e32 v16, v16, v16
	v_mul_f32_e32 v17, v17, v17
	v_fmac_f32_e32 v16, v15, v15
	v_fmac_f32_e32 v17, v26, v26
	global_load_dwordx4 v[8:11], v[12:13], off offset:-1024 nt
	s_waitcnt vmcnt(0)
	v_cvt_pk_bf16_f32 v12, v8, v9
	v_cvt_pk_bf16_f32 v13, v10, v11
	v_add_f32_e32 v15, v16, v17
	global_store_dwordx2 v[2:3], v[12:13], off offset:-1024 nt
	v_add_f32_e32 v14, v14, v15
	v_lshlrev_b32_e32 v15, 16, v12
	v_and_b32_e32 v12, 0xffff0000, v12
	v_lshlrev_b32_e32 v16, 16, v13
	v_and_b32_e32 v13, 0xffff0000, v13
	v_mul_f32_e32 v12, v12, v12
	v_mul_f32_e32 v13, v13, v13
	v_fmac_f32_e32 v12, v15, v15
	v_fmac_f32_e32 v13, v16, v16
	v_add_f32_e32 v12, v12, v13
	global_load_dwordx4 v[8:11], v[6:7], off offset:-4096 nt
	s_waitcnt vmcnt(0)
	v_cvt_pk_bf16_f32 v18, v8, v9
	v_cvt_pk_bf16_f32 v19, v10, v11
	v_add_f32_e32 v12, v14, v12
	v_and_b32_e32 v14, 0xffff0000, v18
	v_and_b32_e32 v16, 0xffff0000, v19
	v_lshlrev_b32_e32 v13, 16, v18
	v_lshlrev_b32_e32 v15, 16, v19
	v_mul_f32_e32 v14, v14, v14
	v_mul_f32_e32 v16, v16, v16
	global_store_dwordx2 v[2:3], v[18:19], off offset:-512 nt
	v_fmac_f32_e32 v14, v13, v13
	v_fmac_f32_e32 v16, v15, v15
	global_load_dwordx4 v[8:11], v[6:7], off offset:-3072 nt
	s_waitcnt vmcnt(0)
	v_cvt_pk_bf16_f32 v20, v8, v9
	v_cvt_pk_bf16_f32 v21, v10, v11
	v_add_f32_e32 v13, v14, v16
	v_and_b32_e32 v14, 0xffff0000, v20
	v_and_b32_e32 v16, 0xffff0000, v21
	v_add_f32_e32 v12, v12, v13
	v_lshlrev_b32_e32 v13, 16, v20
	v_lshlrev_b32_e32 v15, 16, v21
	v_mul_f32_e32 v14, v14, v14
	v_mul_f32_e32 v16, v16, v16
	global_store_dwordx2 v[2:3], v[20:21], off nt
	v_fmac_f32_e32 v14, v13, v13
	v_fmac_f32_e32 v16, v15, v15
	global_load_dwordx4 v[8:11], v[6:7], off offset:-2048 nt
	s_waitcnt vmcnt(0)
	v_cvt_pk_bf16_f32 v22, v8, v9
	v_cvt_pk_bf16_f32 v23, v10, v11
	v_add_f32_e32 v13, v14, v16
	v_and_b32_e32 v14, 0xffff0000, v22
	v_and_b32_e32 v16, 0xffff0000, v23
	v_add_f32_e32 v12, v12, v13
	v_lshlrev_b32_e32 v13, 16, v22
	v_lshlrev_b32_e32 v15, 16, v23
	v_mul_f32_e32 v14, v14, v14
	v_mul_f32_e32 v16, v16, v16
	global_store_dwordx2 v[2:3], v[22:23], off offset:512 nt
	v_fmac_f32_e32 v14, v13, v13
	v_fmac_f32_e32 v16, v15, v15
	global_load_dwordx4 v[8:11], v[6:7], off offset:-1024 nt
	s_waitcnt vmcnt(0)
	v_cvt_pk_bf16_f32 v24, v8, v9
	v_cvt_pk_bf16_f32 v25, v10, v11
	v_add_f32_e32 v13, v14, v16
	v_and_b32_e32 v14, 0xffff0000, v24
	v_and_b32_e32 v16, 0xffff0000, v25
	v_add_f32_e32 v12, v12, v13
	v_lshlrev_b32_e32 v13, 16, v24
	v_lshlrev_b32_e32 v15, 16, v25
	v_mul_f32_e32 v14, v14, v14
	v_mul_f32_e32 v16, v16, v16
	global_store_dwordx2 v[2:3], v[24:25], off offset:1024 nt
	v_fmac_f32_e32 v14, v13, v13
	v_fmac_f32_e32 v16, v15, v15
	global_load_dwordx4 v[8:11], v[6:7], off nt
	v_add_f32_e32 v13, v14, v16
	v_add_f32_e32 v14, v12, v13
	s_waitcnt vmcnt(0)
	v_cvt_pk_bf16_f32 v12, v8, v9
	v_cvt_pk_bf16_f32 v13, v10, v11
	v_cmp_lt_i32_e32 vcc, v220, v219
	v_and_b32_e32 v9, 0xffff0000, v12
	v_and_b32_e32 v11, 0xffff0000, v13
	v_lshlrev_b32_e32 v8, 16, v12
	v_lshlrev_b32_e32 v10, 16, v13
	v_mul_f32_e32 v9, v9, v9
	v_mul_f32_e32 v11, v11, v11
	v_fmac_f32_e32 v9, v8, v8
	v_fmac_f32_e32 v11, v10, v10
	v_cndmask_b32_e32 v0, v218, v220, vcc
	v_add_f32_e32 v8, v9, v11
	v_lshlrev_b32_e32 v0, 2, v0
	v_add_f32_e32 v8, v14, v8
	ds_bpermute_b32 v0, v0, v8
	v_cmp_lt_i32_e32 vcc, v221, v219
	global_store_dwordx2 v[2:3], v[12:13], off offset:1536 nt
	s_waitcnt lgkmcnt(0)
	v_add_f32_e32 v0, v8, v0
	v_cndmask_b32_e32 v9, v218, v221, vcc
	v_lshlrev_b32_e32 v9, 2, v9
	ds_bpermute_b32 v8, v9, v0
	v_cmp_lt_i32_e32 vcc, v222, v219
	s_waitcnt lgkmcnt(0)
	v_add_f32_e32 v0, v0, v8
	v_cndmask_b32_e32 v9, v218, v222, vcc
	v_lshlrev_b32_e32 v9, 2, v9
	ds_bpermute_b32 v8, v9, v0
	v_cmp_lt_i32_e32 vcc, v223, v219
	s_waitcnt lgkmcnt(0)
	v_add_f32_e32 v0, v0, v8
	v_cndmask_b32_e32 v9, v218, v223, vcc
	v_lshlrev_b32_e32 v9, 2, v9
	ds_bpermute_b32 v8, v9, v0
	v_cmp_lt_i32_e32 vcc, v224, v219
	s_waitcnt lgkmcnt(0)
	v_add_f32_e32 v0, v0, v8
	v_cndmask_b32_e32 v9, v218, v224, vcc
	v_lshlrev_b32_e32 v9, 2, v9
	ds_bpermute_b32 v8, v9, v0
	v_cmp_lt_i32_e32 vcc, v225, v219
	s_waitcnt lgkmcnt(0)
	v_add_f32_e32 v0, v0, v8
	v_cndmask_b32_e32 v9, v218, v225, vcc
	v_lshlrev_b32_e32 v8, 2, v9
	ds_bpermute_b32 v8, v8, v0
	s_and_saveexec_b64 s[18:19], s[38:39]
	s_cbranch_execz .LBB0_251
	s_waitcnt lgkmcnt(0)
	v_add_f32_e32 v0, v0, v8
	v_cndmask_b32_e64 v0, 0, v0, s[40:41]
	global_store_dword v[4:5], v0, off
	s_branch .LBB0_251
